# GEMM K-loops: back edge rotated, loop-edge SALU and next iteration's head block issued before the iteration's last barrier
# baseline (speedup 1.0000x reference)
.Lkrot_183:
	ds_read_b128 v[118:121], v130
	ds_read_b128 v[122:125], v130 offset:1024
	ds_read_b128 v[126:129], v130 offset:2048
	ds_read_b128 v[130:133], v130 offset:3072
	ds_read_b128 v[134:137], v150
	ds_read_b128 v[138:141], v150 offset:1024
	ds_read_b128 v[142:145], v150 offset:2048
	ds_read_b128 v[150:153], v150 offset:3072
	v_lshl_add_u64 v[196:197], s[4:5], 0, v[186:187]
	s_add_i32 m0, s74, 0xc000
	ds_read_b128 v[162:165], v211
	ds_read_b128 v[166:169], v211 offset:1024
	ds_read_b128 v[170:173], v211 offset:2048
	ds_read_b128 v[174:177], v211 offset:3072
	ds_read_b128 v[188:191], v211 offset:4096
	ds_read_b128 v[192:195], v211 offset:5120
	ds_read_b128 v[212:215], v211 offset:6144
	ds_read_b128 v[238:241], v211 offset:7168
	global_load_lds_dwordx4 v[196:197], off
	v_lshl_add_u64 v[196:197], s[4:5], 0, v[184:185]
	s_add_i32 m0, s74, 0xe000
	s_nop 0
	global_load_lds_dwordx4 v[196:197], off
	s_waitcnt vmcnt(8)
	s_waitcnt lgkmcnt(0)
	s_barrier
	s_setprio 1
	s_waitcnt lgkmcnt(0)
	v_mfma_f32_16x16x32_bf16 v[158:161], v[118:121], v[162:165], v[158:161]
	v_mfma_f32_16x16x32_bf16 v[62:65], v[126:129], v[162:165], v[62:65]
	v_mfma_f32_16x16x32_bf16 v[146:149], v[118:121], v[170:173], v[146:149]
	v_mfma_f32_16x16x32_bf16 v[54:57], v[126:129], v[170:173], v[54:57]
	v_mfma_f32_16x16x32_bf16 v[110:113], v[118:121], v[188:191], v[110:113]
	v_mfma_f32_16x16x32_bf16 v[46:49], v[126:129], v[188:191], v[46:49]
	v_mfma_f32_16x16x32_bf16 v[102:105], v[118:121], v[212:215], v[102:105]
	v_mfma_f32_16x16x32_bf16 v[38:41], v[126:129], v[212:215], v[38:41]
	v_mfma_f32_16x16x32_bf16 v[158:161], v[122:125], v[166:169], v[158:161]
	v_mfma_f32_16x16x32_bf16 v[62:65], v[130:133], v[166:169], v[62:65]
	v_mfma_f32_16x16x32_bf16 v[146:149], v[122:125], v[174:177], v[146:149]
	v_mfma_f32_16x16x32_bf16 v[54:57], v[130:133], v[174:177], v[54:57]
	v_mfma_f32_16x16x32_bf16 v[110:113], v[122:125], v[192:195], v[110:113]
	v_mfma_f32_16x16x32_bf16 v[46:49], v[130:133], v[192:195], v[46:49]
	v_mfma_f32_16x16x32_bf16 v[102:105], v[122:125], v[238:241], v[102:105]
	v_mfma_f32_16x16x32_bf16 v[38:41], v[130:133], v[238:241], v[38:41]
	s_setprio 0
	s_setprio 1
	v_mfma_f32_16x16x32_bf16 v[154:157], v[134:137], v[162:165], v[154:157]
	v_mfma_f32_16x16x32_bf16 v[58:61], v[142:145], v[162:165], v[58:61]
	v_mfma_f32_16x16x32_bf16 v[114:117], v[134:137], v[170:173], v[114:117]
	v_mfma_f32_16x16x32_bf16 v[50:53], v[142:145], v[170:173], v[50:53]
	v_mfma_f32_16x16x32_bf16 v[106:109], v[134:137], v[188:191], v[106:109]
	v_mfma_f32_16x16x32_bf16 v[42:45], v[142:145], v[188:191], v[42:45]
	v_mfma_f32_16x16x32_bf16 v[98:101], v[134:137], v[212:215], v[98:101]
	v_mfma_f32_16x16x32_bf16 v[34:37], v[142:145], v[212:215], v[34:37]
	v_mfma_f32_16x16x32_bf16 v[154:157], v[138:141], v[166:169], v[154:157]
	v_mfma_f32_16x16x32_bf16 v[58:61], v[150:153], v[166:169], v[58:61]
	v_mfma_f32_16x16x32_bf16 v[114:117], v[138:141], v[174:177], v[114:117]
	v_mfma_f32_16x16x32_bf16 v[50:53], v[150:153], v[174:177], v[50:53]
	v_mfma_f32_16x16x32_bf16 v[106:109], v[138:141], v[192:195], v[106:109]
	v_mfma_f32_16x16x32_bf16 v[42:45], v[150:153], v[192:195], v[42:45]
	v_mfma_f32_16x16x32_bf16 v[98:101], v[138:141], v[238:241], v[98:101]
	v_mfma_f32_16x16x32_bf16 v[34:37], v[150:153], v[238:241], v[34:37]
	s_setprio 0
	s_barrier
	s_add_i32 s6, s15, s49
	v_lshl_add_u64 v[196:197], s[38:39], 0, v[0:1]
	s_mov_b32 m0, s6
	ds_read_b128 v[162:165], v211 offset:16384
	ds_read_b128 v[166:169], v211 offset:17408
	ds_read_b128 v[170:173], v211 offset:18432
	ds_read_b128 v[174:177], v211 offset:19456
	ds_read_b128 v[188:191], v211 offset:20480
	ds_read_b128 v[192:195], v211 offset:21504
	ds_read_b128 v[212:215], v211 offset:22528
	ds_read_b128 v[238:241], v211 offset:23552
	global_load_lds_dwordx4 v[196:197], off
	s_add_i32 m0, s6, 0x2000
	s_add_u32 s6, s38, 0x80000
	v_lshl_add_u64 v[216:217], s[38:39], 0, v[178:179]
	s_addc_u32 s7, s39, 0
	s_add_i32 s15, s76, s49
	global_load_lds_dwordx4 v[216:217], off
	v_lshl_add_u64 v[242:243], s[6:7], 0, v[0:1]
	s_mov_b32 m0, s15
	v_lshl_add_u64 v[244:245], s[40:41], 0, v[180:181]
	global_load_lds_dwordx4 v[242:243], off
	v_lshl_add_u64 v[242:243], s[6:7], 0, v[178:179]
	s_add_i32 m0, s15, 0x2000
	s_nop 0
	global_load_lds_dwordx4 v[242:243], off
	v_lshl_add_u64 v[242:243], s[40:41], 0, v[182:183]
	s_mov_b32 m0, s74
	s_nop 0
	global_load_lds_dwordx4 v[242:243], off
	s_mov_b32 m0, s75
	s_nop 0
	global_load_lds_dwordx4 v[244:245], off
	s_waitcnt vmcnt(8)
	s_waitcnt lgkmcnt(0)
	s_barrier
	s_setprio 1
	s_waitcnt lgkmcnt(0)
	v_mfma_f32_16x16x32_bf16 v[94:97], v[118:121], v[162:165], v[94:97]
	v_mfma_f32_16x16x32_bf16 v[30:33], v[126:129], v[162:165], v[30:33]
	v_mfma_f32_16x16x32_bf16 v[86:89], v[118:121], v[170:173], v[86:89]
	v_mfma_f32_16x16x32_bf16 v[22:25], v[126:129], v[170:173], v[22:25]
	v_mfma_f32_16x16x32_bf16 v[78:81], v[118:121], v[188:191], v[78:81]
	v_mfma_f32_16x16x32_bf16 v[14:17], v[126:129], v[188:191], v[14:17]
	v_mfma_f32_16x16x32_bf16 v[66:69], v[118:121], v[212:215], v[66:69]
	v_mfma_f32_16x16x32_bf16 v[2:5], v[126:129], v[212:215], v[2:5]
	v_mfma_f32_16x16x32_bf16 v[94:97], v[122:125], v[166:169], v[94:97]
	v_mfma_f32_16x16x32_bf16 v[30:33], v[130:133], v[166:169], v[30:33]
	v_mfma_f32_16x16x32_bf16 v[86:89], v[122:125], v[174:177], v[86:89]
	v_mfma_f32_16x16x32_bf16 v[22:25], v[130:133], v[174:177], v[22:25]
	v_mfma_f32_16x16x32_bf16 v[78:81], v[122:125], v[192:195], v[78:81]
	v_mfma_f32_16x16x32_bf16 v[14:17], v[130:133], v[192:195], v[14:17]
	v_mfma_f32_16x16x32_bf16 v[66:69], v[122:125], v[238:241], v[66:69]
	v_mfma_f32_16x16x32_bf16 v[2:5], v[130:133], v[238:241], v[2:5]
	s_setprio 0
	s_setprio 1
	v_mfma_f32_16x16x32_bf16 v[90:93], v[134:137], v[162:165], v[90:93]
	v_mfma_f32_16x16x32_bf16 v[26:29], v[142:145], v[162:165], v[26:29]
	v_mfma_f32_16x16x32_bf16 v[82:85], v[134:137], v[170:173], v[82:85]
	v_mfma_f32_16x16x32_bf16 v[18:21], v[142:145], v[170:173], v[18:21]
	v_mfma_f32_16x16x32_bf16 v[74:77], v[134:137], v[188:191], v[74:77]
	v_mfma_f32_16x16x32_bf16 v[10:13], v[142:145], v[188:191], v[10:13]
	v_mfma_f32_16x16x32_bf16 v[70:73], v[134:137], v[212:215], v[70:73]
	v_mfma_f32_16x16x32_bf16 v[6:9], v[142:145], v[212:215], v[6:9]
	v_mfma_f32_16x16x32_bf16 v[90:93], v[138:141], v[166:169], v[90:93]
	v_mfma_f32_16x16x32_bf16 v[26:29], v[150:153], v[166:169], v[26:29]
	v_mfma_f32_16x16x32_bf16 v[82:85], v[138:141], v[174:177], v[82:85]
	v_mfma_f32_16x16x32_bf16 v[18:21], v[150:153], v[174:177], v[18:21]
	v_mfma_f32_16x16x32_bf16 v[74:77], v[138:141], v[192:195], v[74:77]
	v_mfma_f32_16x16x32_bf16 v[10:13], v[150:153], v[192:195], v[10:13]
	v_mfma_f32_16x16x32_bf16 v[70:73], v[138:141], v[238:241], v[70:73]
	v_mfma_f32_16x16x32_bf16 v[6:9], v[150:153], v[238:241], v[6:9]
	s_setprio 0
	s_barrier
	s_add_i32 s15, 0, 0x18000
	s_add_i32 s76, 0, 0x1c000
	v_add_u32_e32 v130, s15, v210
	v_add_u32_e32 v150, s76, v210
	ds_read_b128 v[118:121], v130
	ds_read_b128 v[122:125], v130 offset:1024
	ds_read_b128 v[126:129], v130 offset:2048
	ds_read_b128 v[130:133], v130 offset:3072
	ds_read_b128 v[134:137], v150
	ds_read_b128 v[138:141], v150 offset:1024
	ds_read_b128 v[142:145], v150 offset:2048
	ds_read_b128 v[150:153], v150 offset:3072
	s_add_u32 s6, s40, 0x80000
	s_addc_u32 s7, s41, 0
	s_mov_b32 m0, s78
	v_lshl_add_u64 v[246:247], s[6:7], 0, v[182:183]
	ds_read_b128 v[162:165], v211 offset:32768
	ds_read_b128 v[166:169], v211 offset:33792
	ds_read_b128 v[170:173], v211 offset:34816
	ds_read_b128 v[174:177], v211 offset:35840
	ds_read_b128 v[188:191], v211 offset:36864
	ds_read_b128 v[192:195], v211 offset:37888
	ds_read_b128 v[212:215], v211 offset:38912
	ds_read_b128 v[238:241], v211 offset:39936
	global_load_lds_dwordx4 v[246:247], off
	v_lshl_add_u64 v[246:247], s[6:7], 0, v[180:181]
	s_mov_b32 m0, s79
	s_nop 0
	global_load_lds_dwordx4 v[246:247], off
	s_waitcnt vmcnt(8)
	s_waitcnt lgkmcnt(0)
	s_barrier
	s_setprio 1
	s_waitcnt lgkmcnt(0)
	v_mfma_f32_16x16x32_bf16 v[158:161], v[118:121], v[162:165], v[158:161]
	v_mfma_f32_16x16x32_bf16 v[62:65], v[126:129], v[162:165], v[62:65]
	v_mfma_f32_16x16x32_bf16 v[146:149], v[118:121], v[170:173], v[146:149]
	v_mfma_f32_16x16x32_bf16 v[54:57], v[126:129], v[170:173], v[54:57]
	v_mfma_f32_16x16x32_bf16 v[110:113], v[118:121], v[188:191], v[110:113]
	v_mfma_f32_16x16x32_bf16 v[46:49], v[126:129], v[188:191], v[46:49]
	v_mfma_f32_16x16x32_bf16 v[102:105], v[118:121], v[212:215], v[102:105]
	v_mfma_f32_16x16x32_bf16 v[38:41], v[126:129], v[212:215], v[38:41]
	v_mfma_f32_16x16x32_bf16 v[158:161], v[122:125], v[166:169], v[158:161]
	v_mfma_f32_16x16x32_bf16 v[62:65], v[130:133], v[166:169], v[62:65]
	v_mfma_f32_16x16x32_bf16 v[146:149], v[122:125], v[174:177], v[146:149]
	v_mfma_f32_16x16x32_bf16 v[54:57], v[130:133], v[174:177], v[54:57]
	v_mfma_f32_16x16x32_bf16 v[110:113], v[122:125], v[192:195], v[110:113]
	v_mfma_f32_16x16x32_bf16 v[46:49], v[130:133], v[192:195], v[46:49]
	v_mfma_f32_16x16x32_bf16 v[102:105], v[122:125], v[238:241], v[102:105]
	v_mfma_f32_16x16x32_bf16 v[38:41], v[130:133], v[238:241], v[38:41]
	s_setprio 0
	s_setprio 1
	v_mfma_f32_16x16x32_bf16 v[154:157], v[134:137], v[162:165], v[154:157]
	v_mfma_f32_16x16x32_bf16 v[58:61], v[142:145], v[162:165], v[58:61]
	v_mfma_f32_16x16x32_bf16 v[114:117], v[134:137], v[170:173], v[114:117]
	v_mfma_f32_16x16x32_bf16 v[50:53], v[142:145], v[170:173], v[50:53]
	v_mfma_f32_16x16x32_bf16 v[106:109], v[134:137], v[188:191], v[106:109]
	v_mfma_f32_16x16x32_bf16 v[42:45], v[142:145], v[188:191], v[42:45]
	v_mfma_f32_16x16x32_bf16 v[98:101], v[134:137], v[212:215], v[98:101]
	v_mfma_f32_16x16x32_bf16 v[34:37], v[142:145], v[212:215], v[34:37]
	v_mfma_f32_16x16x32_bf16 v[154:157], v[138:141], v[166:169], v[154:157]
	v_mfma_f32_16x16x32_bf16 v[58:61], v[150:153], v[166:169], v[58:61]
	v_mfma_f32_16x16x32_bf16 v[114:117], v[138:141], v[174:177], v[114:117]
	v_mfma_f32_16x16x32_bf16 v[50:53], v[150:153], v[174:177], v[50:53]
	v_mfma_f32_16x16x32_bf16 v[106:109], v[138:141], v[192:195], v[106:109]
	v_mfma_f32_16x16x32_bf16 v[42:45], v[150:153], v[192:195], v[42:45]
	v_mfma_f32_16x16x32_bf16 v[98:101], v[138:141], v[238:241], v[98:101]
	v_mfma_f32_16x16x32_bf16 v[34:37], v[150:153], v[238:241], v[34:37]
	s_setprio 0
	s_barrier
	s_add_i32 s6, s15, s49
	v_lshl_add_u64 v[196:197], v[196:197], 0, s[36:37]
	s_mov_b32 m0, s6
	ds_read_b128 v[162:165], v211 offset:49152
	ds_read_b128 v[166:169], v211 offset:50176
	ds_read_b128 v[170:173], v211 offset:51200
	ds_read_b128 v[174:177], v211 offset:52224
	ds_read_b128 v[188:191], v211 offset:53248
	ds_read_b128 v[192:195], v211 offset:54272
	ds_read_b128 v[212:215], v211 offset:55296
	ds_read_b128 v[238:241], v211 offset:56320
	global_load_lds_dwordx4 v[196:197], off
	s_add_i32 m0, s6, 0x2000
	s_add_u32 s6, s38, 0x80080
	v_lshl_add_u64 v[196:197], v[216:217], 0, s[36:37]
	s_addc_u32 s7, s39, 0
	s_add_i32 s15, s76, s49
	global_load_lds_dwordx4 v[196:197], off
	v_lshl_add_u64 v[196:197], s[6:7], 0, v[0:1]
	s_mov_b32 m0, s15
	s_nop 0
	global_load_lds_dwordx4 v[196:197], off
	v_lshl_add_u64 v[196:197], s[6:7], 0, v[178:179]
	s_add_i32 m0, s15, 0x2000
	s_nop 0
	global_load_lds_dwordx4 v[196:197], off
	v_lshl_add_u64 v[196:197], v[242:243], 0, s[36:37]
	s_mov_b32 m0, s10
	s_nop 0
	global_load_lds_dwordx4 v[196:197], off
	v_lshl_add_u64 v[196:197], v[244:245], 0, s[36:37]
	s_mov_b32 m0, s11
	s_nop 0
	global_load_lds_dwordx4 v[196:197], off
	s_waitcnt vmcnt(8)
	s_waitcnt lgkmcnt(0)
	s_barrier
	s_setprio 1
	s_waitcnt lgkmcnt(0)
	v_mfma_f32_16x16x32_bf16 v[94:97], v[118:121], v[162:165], v[94:97]
	v_mfma_f32_16x16x32_bf16 v[30:33], v[126:129], v[162:165], v[30:33]
	v_mfma_f32_16x16x32_bf16 v[86:89], v[118:121], v[170:173], v[86:89]
	v_mfma_f32_16x16x32_bf16 v[22:25], v[126:129], v[170:173], v[22:25]
	v_mfma_f32_16x16x32_bf16 v[78:81], v[118:121], v[188:191], v[78:81]
	v_mfma_f32_16x16x32_bf16 v[14:17], v[126:129], v[188:191], v[14:17]
	v_mfma_f32_16x16x32_bf16 v[66:69], v[118:121], v[212:215], v[66:69]
	v_mfma_f32_16x16x32_bf16 v[2:5], v[126:129], v[212:215], v[2:5]
	v_mfma_f32_16x16x32_bf16 v[94:97], v[122:125], v[166:169], v[94:97]
	v_mfma_f32_16x16x32_bf16 v[30:33], v[130:133], v[166:169], v[30:33]
	v_mfma_f32_16x16x32_bf16 v[86:89], v[122:125], v[174:177], v[86:89]
	v_mfma_f32_16x16x32_bf16 v[22:25], v[130:133], v[174:177], v[22:25]
	v_mfma_f32_16x16x32_bf16 v[78:81], v[122:125], v[192:195], v[78:81]
	v_mfma_f32_16x16x32_bf16 v[14:17], v[130:133], v[192:195], v[14:17]
	v_mfma_f32_16x16x32_bf16 v[66:69], v[122:125], v[238:241], v[66:69]
	v_mfma_f32_16x16x32_bf16 v[2:5], v[130:133], v[238:241], v[2:5]
	s_setprio 0
	s_setprio 1
	v_mfma_f32_16x16x32_bf16 v[90:93], v[134:137], v[162:165], v[90:93]
	v_mfma_f32_16x16x32_bf16 v[26:29], v[142:145], v[162:165], v[26:29]
	v_mfma_f32_16x16x32_bf16 v[82:85], v[134:137], v[170:173], v[82:85]
	v_mfma_f32_16x16x32_bf16 v[18:21], v[142:145], v[170:173], v[18:21]
	v_mfma_f32_16x16x32_bf16 v[74:77], v[134:137], v[188:191], v[74:77]
	v_mfma_f32_16x16x32_bf16 v[10:13], v[142:145], v[188:191], v[10:13]
	v_mfma_f32_16x16x32_bf16 v[70:73], v[134:137], v[212:215], v[70:73]
	v_mfma_f32_16x16x32_bf16 v[6:9], v[142:145], v[212:215], v[6:9]
	v_mfma_f32_16x16x32_bf16 v[90:93], v[138:141], v[166:169], v[90:93]
	v_mfma_f32_16x16x32_bf16 v[26:29], v[150:153], v[166:169], v[26:29]
	v_mfma_f32_16x16x32_bf16 v[82:85], v[138:141], v[174:177], v[82:85]
	v_mfma_f32_16x16x32_bf16 v[18:21], v[150:153], v[174:177], v[18:21]
	v_mfma_f32_16x16x32_bf16 v[74:77], v[138:141], v[192:195], v[74:77]
	v_mfma_f32_16x16x32_bf16 v[10:13], v[150:153], v[192:195], v[10:13]
	v_mfma_f32_16x16x32_bf16 v[70:73], v[138:141], v[238:241], v[70:73]
	v_mfma_f32_16x16x32_bf16 v[6:9], v[150:153], v[238:241], v[6:9]
	s_setprio 0
	s_add_i32 s14, s14, 2
	s_add_u32 s69, s69, 0x100
	s_addc_u32 s71, s71, 0
	s_add_u32 s4, s4, 0x100
	s_addc_u32 s5, s5, 0
	s_add_u32 s6, s4, 0xfff80080
	s_addc_u32 s7, s5, -1
	s_add_i32 s15, 0, 0x10000
	s_cmp_eq_u32 s14, 28
	s_cselect_b32 s41, s8, s7
	s_cselect_b32 s40, s9, s6
	s_cselect_b32 s39, s42, s71
	s_cselect_b32 s38, s43, s69
	s_add_i32 s76, 0, 0x14000
	v_add_u32_e32 v130, s15, v210
	v_add_u32_e32 v150, s76, v210
	s_cmp_gt_u32 s14, 29
	s_barrier
	s_cbranch_scc0 .Lkrot_183
	v_readlane_b32 s4, v253, 30
	v_readlane_b32 s5, v253, 31
	s_and_b64 vcc, exec, s[4:5]
	s_cbranch_vccz .LBB0_186
	s_barrier

.Lkrot_371:
	ds_read_b128 v[122:125], v142
	ds_read_b128 v[126:129], v142 offset:1024
	ds_read_b128 v[134:137], v142 offset:2048
	ds_read_b128 v[142:145], v142 offset:3072
	ds_read_b128 v[146:149], v158
	ds_read_b128 v[150:153], v158 offset:1024
	ds_read_b128 v[154:157], v158 offset:2048
	ds_read_b128 v[158:161], v158 offset:3072
	v_lshl_add_u64 v[196:197], s[4:5], 0, v[170:171]
	s_add_i32 m0, s78, 0xc000
	ds_read_b128 v[172:175], v240
	ds_read_b128 v[176:179], v240 offset:1024
	ds_read_b128 v[180:183], v240 offset:2048
	ds_read_b128 v[184:187], v240 offset:3072
	ds_read_b128 v[188:191], v240 offset:4096
	ds_read_b128 v[192:195], v240 offset:5120
	ds_read_b128 v[208:211], v240 offset:6144
	ds_read_b128 v[212:215], v240 offset:7168
	global_load_lds_dwordx4 v[196:197], off
	v_lshl_add_u64 v[196:197], s[4:5], 0, v[168:169]
	s_add_i32 m0, s78, 0xe000
	s_nop 0
	global_load_lds_dwordx4 v[196:197], off
	s_waitcnt vmcnt(8)
	s_waitcnt lgkmcnt(0)
	s_barrier
	s_setprio 1
	s_waitcnt lgkmcnt(0)
	v_mfma_f32_16x16x32_bf16 v[138:141], v[122:125], v[172:175], v[138:141]
	v_mfma_f32_16x16x32_bf16 v[130:133], v[134:137], v[172:175], v[130:133]
	v_mfma_f32_16x16x32_bf16 v[118:121], v[122:125], v[180:183], v[118:121]
	v_mfma_f32_16x16x32_bf16 v[114:117], v[134:137], v[180:183], v[114:117]
	v_mfma_f32_16x16x32_bf16 v[110:113], v[122:125], v[188:191], v[110:113]
	v_mfma_f32_16x16x32_bf16 v[106:109], v[134:137], v[188:191], v[106:109]
	v_mfma_f32_16x16x32_bf16 v[102:105], v[122:125], v[208:211], v[102:105]
	v_mfma_f32_16x16x32_bf16 v[98:101], v[134:137], v[208:211], v[98:101]
	v_mfma_f32_16x16x32_bf16 v[138:141], v[126:129], v[176:179], v[138:141]
	v_mfma_f32_16x16x32_bf16 v[130:133], v[142:145], v[176:179], v[130:133]
	v_mfma_f32_16x16x32_bf16 v[118:121], v[126:129], v[184:187], v[118:121]
	v_mfma_f32_16x16x32_bf16 v[114:117], v[142:145], v[184:187], v[114:117]
	v_mfma_f32_16x16x32_bf16 v[110:113], v[126:129], v[192:195], v[110:113]
	v_mfma_f32_16x16x32_bf16 v[106:109], v[142:145], v[192:195], v[106:109]
	v_mfma_f32_16x16x32_bf16 v[102:105], v[126:129], v[212:215], v[102:105]
	v_mfma_f32_16x16x32_bf16 v[98:101], v[142:145], v[212:215], v[98:101]
	s_setprio 0
	s_setprio 1
	v_mfma_f32_16x16x32_bf16 v[62:65], v[146:149], v[172:175], v[62:65]
	v_mfma_f32_16x16x32_bf16 v[58:61], v[154:157], v[172:175], v[58:61]
	v_mfma_f32_16x16x32_bf16 v[54:57], v[146:149], v[180:183], v[54:57]
	v_mfma_f32_16x16x32_bf16 v[50:53], v[154:157], v[180:183], v[50:53]
	v_mfma_f32_16x16x32_bf16 v[46:49], v[146:149], v[188:191], v[46:49]
	v_mfma_f32_16x16x32_bf16 v[42:45], v[154:157], v[188:191], v[42:45]
	v_mfma_f32_16x16x32_bf16 v[38:41], v[146:149], v[208:211], v[38:41]
	v_mfma_f32_16x16x32_bf16 v[34:37], v[154:157], v[208:211], v[34:37]
	v_mfma_f32_16x16x32_bf16 v[62:65], v[150:153], v[176:179], v[62:65]
	v_mfma_f32_16x16x32_bf16 v[58:61], v[158:161], v[176:179], v[58:61]
	v_mfma_f32_16x16x32_bf16 v[54:57], v[150:153], v[184:187], v[54:57]
	v_mfma_f32_16x16x32_bf16 v[50:53], v[158:161], v[184:187], v[50:53]
	v_mfma_f32_16x16x32_bf16 v[46:49], v[150:153], v[192:195], v[46:49]
	v_mfma_f32_16x16x32_bf16 v[42:45], v[158:161], v[192:195], v[42:45]
	v_mfma_f32_16x16x32_bf16 v[38:41], v[150:153], v[212:215], v[38:41]
	v_mfma_f32_16x16x32_bf16 v[34:37], v[158:161], v[212:215], v[34:37]
	s_setprio 0
	s_barrier
	s_add_i32 s40, s40, s49
	v_lshl_add_u64 v[196:197], s[6:7], 0, v[0:1]
	s_mov_b32 m0, s40
	ds_read_b128 v[172:175], v240 offset:16384
	ds_read_b128 v[176:179], v240 offset:17408
	ds_read_b128 v[180:183], v240 offset:18432
	ds_read_b128 v[184:187], v240 offset:19456
	ds_read_b128 v[188:191], v240 offset:20480
	ds_read_b128 v[192:195], v240 offset:21504
	ds_read_b128 v[208:211], v240 offset:22528
	ds_read_b128 v[212:215], v240 offset:23552
	global_load_lds_dwordx4 v[196:197], off
	s_add_i32 m0, s40, 0x2000
	v_lshl_add_u64 v[216:217], s[6:7], 0, v[162:163]
	s_add_u32 s6, s6, s80
	s_addc_u32 s7, s7, 0
	s_add_i32 s14, s14, s49
	global_load_lds_dwordx4 v[216:217], off
	v_lshl_add_u64 v[242:243], s[6:7], 0, v[0:1]
	s_mov_b32 m0, s14
	v_lshl_add_u64 v[244:245], s[6:7], 0, v[162:163]
	global_load_lds_dwordx4 v[242:243], off
	s_add_i32 m0, s14, 0x2000
	v_lshl_add_u64 v[246:247], s[38:39], 0, v[166:167]
	global_load_lds_dwordx4 v[244:245], off
	s_mov_b32 m0, s78
	v_lshl_add_u64 v[248:249], s[38:39], 0, v[164:165]
	global_load_lds_dwordx4 v[246:247], off
	s_mov_b32 m0, s79
	s_nop 0
	global_load_lds_dwordx4 v[248:249], off
	s_waitcnt vmcnt(8)
	s_waitcnt lgkmcnt(0)
	s_barrier
	s_setprio 1
	s_waitcnt lgkmcnt(0)
	v_mfma_f32_16x16x32_bf16 v[94:97], v[122:125], v[172:175], v[94:97]
	v_mfma_f32_16x16x32_bf16 v[90:93], v[134:137], v[172:175], v[90:93]
	v_mfma_f32_16x16x32_bf16 v[86:89], v[122:125], v[180:183], v[86:89]
	v_mfma_f32_16x16x32_bf16 v[82:85], v[134:137], v[180:183], v[82:85]
	v_mfma_f32_16x16x32_bf16 v[78:81], v[122:125], v[188:191], v[78:81]
	v_mfma_f32_16x16x32_bf16 v[74:77], v[134:137], v[188:191], v[74:77]
	v_mfma_f32_16x16x32_bf16 v[70:73], v[122:125], v[208:211], v[70:73]
	v_mfma_f32_16x16x32_bf16 v[66:69], v[134:137], v[208:211], v[66:69]
	v_mfma_f32_16x16x32_bf16 v[94:97], v[126:129], v[176:179], v[94:97]
	v_mfma_f32_16x16x32_bf16 v[90:93], v[142:145], v[176:179], v[90:93]
	v_mfma_f32_16x16x32_bf16 v[86:89], v[126:129], v[184:187], v[86:89]
	v_mfma_f32_16x16x32_bf16 v[82:85], v[142:145], v[184:187], v[82:85]
	v_mfma_f32_16x16x32_bf16 v[78:81], v[126:129], v[192:195], v[78:81]
	v_mfma_f32_16x16x32_bf16 v[74:77], v[142:145], v[192:195], v[74:77]
	v_mfma_f32_16x16x32_bf16 v[70:73], v[126:129], v[212:215], v[70:73]
	v_mfma_f32_16x16x32_bf16 v[66:69], v[142:145], v[212:215], v[66:69]
	s_setprio 0
	s_setprio 1
	v_mfma_f32_16x16x32_bf16 v[30:33], v[146:149], v[172:175], v[30:33]
	v_mfma_f32_16x16x32_bf16 v[26:29], v[154:157], v[172:175], v[26:29]
	v_mfma_f32_16x16x32_bf16 v[22:25], v[146:149], v[180:183], v[22:25]
	v_mfma_f32_16x16x32_bf16 v[18:21], v[154:157], v[180:183], v[18:21]
	v_mfma_f32_16x16x32_bf16 v[14:17], v[146:149], v[188:191], v[14:17]
	v_mfma_f32_16x16x32_bf16 v[10:13], v[154:157], v[188:191], v[10:13]
	v_mfma_f32_16x16x32_bf16 v[6:9], v[146:149], v[208:211], v[6:9]
	v_mfma_f32_16x16x32_bf16 v[2:5], v[154:157], v[208:211], v[2:5]
	v_mfma_f32_16x16x32_bf16 v[30:33], v[150:153], v[176:179], v[30:33]
	v_mfma_f32_16x16x32_bf16 v[26:29], v[158:161], v[176:179], v[26:29]
	v_mfma_f32_16x16x32_bf16 v[22:25], v[150:153], v[184:187], v[22:25]
	v_mfma_f32_16x16x32_bf16 v[18:21], v[158:161], v[184:187], v[18:21]
	v_mfma_f32_16x16x32_bf16 v[14:17], v[150:153], v[192:195], v[14:17]
	v_mfma_f32_16x16x32_bf16 v[10:13], v[158:161], v[192:195], v[10:13]
	v_mfma_f32_16x16x32_bf16 v[6:9], v[150:153], v[212:215], v[6:9]
	v_mfma_f32_16x16x32_bf16 v[2:5], v[158:161], v[212:215], v[2:5]
	s_setprio 0
	s_barrier
	s_add_i32 s14, 0, 0x18000
	s_add_i32 s40, 0, 0x1c000
	v_add_u32_e32 v142, s14, v239
	v_add_u32_e32 v158, s40, v239
	ds_read_b128 v[122:125], v142
	ds_read_b128 v[126:129], v142 offset:1024
	ds_read_b128 v[134:137], v142 offset:2048
	ds_read_b128 v[142:145], v142 offset:3072
	ds_read_b128 v[146:149], v158
	ds_read_b128 v[150:153], v158 offset:1024
	ds_read_b128 v[154:157], v158 offset:2048
	ds_read_b128 v[158:161], v158 offset:3072
	s_add_u32 s6, s38, s80
	s_addc_u32 s7, s39, 0
	s_mov_b32 m0, s86
	v_lshl_add_u64 v[250:251], s[6:7], 0, v[166:167]
	ds_read_b128 v[172:175], v240 offset:32768
	ds_read_b128 v[176:179], v240 offset:33792
	ds_read_b128 v[180:183], v240 offset:34816
	ds_read_b128 v[184:187], v240 offset:35840
	ds_read_b128 v[188:191], v240 offset:36864
	ds_read_b128 v[192:195], v240 offset:37888
	ds_read_b128 v[208:211], v240 offset:38912
	ds_read_b128 v[212:215], v240 offset:39936
	global_load_lds_dwordx4 v[250:251], off
	v_lshl_add_u64 v[250:251], s[6:7], 0, v[164:165]
	s_mov_b32 m0, s87
	s_nop 0
	global_load_lds_dwordx4 v[250:251], off
	s_waitcnt vmcnt(8)
	s_waitcnt lgkmcnt(0)
	s_barrier
	s_setprio 1
	s_waitcnt lgkmcnt(0)
	v_mfma_f32_16x16x32_bf16 v[138:141], v[122:125], v[172:175], v[138:141]
	v_mfma_f32_16x16x32_bf16 v[130:133], v[134:137], v[172:175], v[130:133]
	v_mfma_f32_16x16x32_bf16 v[118:121], v[122:125], v[180:183], v[118:121]
	v_mfma_f32_16x16x32_bf16 v[114:117], v[134:137], v[180:183], v[114:117]
	v_mfma_f32_16x16x32_bf16 v[110:113], v[122:125], v[188:191], v[110:113]
	v_mfma_f32_16x16x32_bf16 v[106:109], v[134:137], v[188:191], v[106:109]
	v_mfma_f32_16x16x32_bf16 v[102:105], v[122:125], v[208:211], v[102:105]
	v_mfma_f32_16x16x32_bf16 v[98:101], v[134:137], v[208:211], v[98:101]
	v_mfma_f32_16x16x32_bf16 v[138:141], v[126:129], v[176:179], v[138:141]
	v_mfma_f32_16x16x32_bf16 v[130:133], v[142:145], v[176:179], v[130:133]
	v_mfma_f32_16x16x32_bf16 v[118:121], v[126:129], v[184:187], v[118:121]
	v_mfma_f32_16x16x32_bf16 v[114:117], v[142:145], v[184:187], v[114:117]
	v_mfma_f32_16x16x32_bf16 v[110:113], v[126:129], v[192:195], v[110:113]
	v_mfma_f32_16x16x32_bf16 v[106:109], v[142:145], v[192:195], v[106:109]
	v_mfma_f32_16x16x32_bf16 v[102:105], v[126:129], v[212:215], v[102:105]
	v_mfma_f32_16x16x32_bf16 v[98:101], v[142:145], v[212:215], v[98:101]
	s_setprio 0
	s_setprio 1
	v_mfma_f32_16x16x32_bf16 v[62:65], v[146:149], v[172:175], v[62:65]
	v_mfma_f32_16x16x32_bf16 v[58:61], v[154:157], v[172:175], v[58:61]
	v_mfma_f32_16x16x32_bf16 v[54:57], v[146:149], v[180:183], v[54:57]
	v_mfma_f32_16x16x32_bf16 v[50:53], v[154:157], v[180:183], v[50:53]
	v_mfma_f32_16x16x32_bf16 v[46:49], v[146:149], v[188:191], v[46:49]
	v_mfma_f32_16x16x32_bf16 v[42:45], v[154:157], v[188:191], v[42:45]
	v_mfma_f32_16x16x32_bf16 v[38:41], v[146:149], v[208:211], v[38:41]
	v_mfma_f32_16x16x32_bf16 v[34:37], v[154:157], v[208:211], v[34:37]
	v_mfma_f32_16x16x32_bf16 v[62:65], v[150:153], v[176:179], v[62:65]
	v_mfma_f32_16x16x32_bf16 v[58:61], v[158:161], v[176:179], v[58:61]
	v_mfma_f32_16x16x32_bf16 v[54:57], v[150:153], v[184:187], v[54:57]
	v_mfma_f32_16x16x32_bf16 v[50:53], v[158:161], v[184:187], v[50:53]
	v_mfma_f32_16x16x32_bf16 v[46:49], v[150:153], v[192:195], v[46:49]
	v_mfma_f32_16x16x32_bf16 v[42:45], v[158:161], v[192:195], v[42:45]
	v_mfma_f32_16x16x32_bf16 v[38:41], v[150:153], v[212:215], v[38:41]
	v_mfma_f32_16x16x32_bf16 v[34:37], v[158:161], v[212:215], v[34:37]
	s_setprio 0
	s_barrier
	s_add_i32 s6, s14, s49
	v_lshl_add_u64 v[196:197], v[196:197], 0, s[36:37]
	s_mov_b32 m0, s6
	ds_read_b128 v[172:175], v240 offset:49152
	ds_read_b128 v[176:179], v240 offset:50176
	ds_read_b128 v[180:183], v240 offset:51200
	ds_read_b128 v[184:187], v240 offset:52224
	ds_read_b128 v[188:191], v240 offset:53248
	ds_read_b128 v[192:195], v240 offset:54272
	ds_read_b128 v[208:211], v240 offset:55296
	ds_read_b128 v[212:215], v240 offset:56320
	global_load_lds_dwordx4 v[196:197], off
	v_lshl_add_u64 v[196:197], v[216:217], 0, s[36:37]
	s_add_i32 m0, s6, 0x2000
	s_add_i32 s6, s40, s49
	global_load_lds_dwordx4 v[196:197], off
	v_lshl_add_u64 v[196:197], v[242:243], 0, s[36:37]
	s_mov_b32 m0, s6
	s_nop 0
	global_load_lds_dwordx4 v[196:197], off
	v_lshl_add_u64 v[196:197], v[244:245], 0, s[36:37]
	s_add_i32 m0, s6, 0x2000
	s_nop 0
	global_load_lds_dwordx4 v[196:197], off
	v_lshl_add_u64 v[196:197], v[246:247], 0, s[36:37]
	s_mov_b32 m0, s44
	s_nop 0
	global_load_lds_dwordx4 v[196:197], off
	v_lshl_add_u64 v[196:197], v[248:249], 0, s[36:37]
	s_mov_b32 m0, s45
	s_nop 0
	global_load_lds_dwordx4 v[196:197], off
	s_waitcnt vmcnt(8)
	s_waitcnt lgkmcnt(0)
	s_barrier
	s_setprio 1
	s_waitcnt lgkmcnt(0)
	v_mfma_f32_16x16x32_bf16 v[94:97], v[122:125], v[172:175], v[94:97]
	v_mfma_f32_16x16x32_bf16 v[90:93], v[134:137], v[172:175], v[90:93]
	v_mfma_f32_16x16x32_bf16 v[86:89], v[122:125], v[180:183], v[86:89]
	v_mfma_f32_16x16x32_bf16 v[82:85], v[134:137], v[180:183], v[82:85]
	v_mfma_f32_16x16x32_bf16 v[78:81], v[122:125], v[188:191], v[78:81]
	v_mfma_f32_16x16x32_bf16 v[74:77], v[134:137], v[188:191], v[74:77]
	v_mfma_f32_16x16x32_bf16 v[70:73], v[122:125], v[208:211], v[70:73]
	v_mfma_f32_16x16x32_bf16 v[66:69], v[134:137], v[208:211], v[66:69]
	v_mfma_f32_16x16x32_bf16 v[94:97], v[126:129], v[176:179], v[94:97]
	v_mfma_f32_16x16x32_bf16 v[90:93], v[142:145], v[176:179], v[90:93]
	v_mfma_f32_16x16x32_bf16 v[86:89], v[126:129], v[184:187], v[86:89]
	v_mfma_f32_16x16x32_bf16 v[82:85], v[142:145], v[184:187], v[82:85]
	v_mfma_f32_16x16x32_bf16 v[78:81], v[126:129], v[192:195], v[78:81]
	v_mfma_f32_16x16x32_bf16 v[74:77], v[142:145], v[192:195], v[74:77]
	v_mfma_f32_16x16x32_bf16 v[70:73], v[126:129], v[212:215], v[70:73]
	v_mfma_f32_16x16x32_bf16 v[66:69], v[142:145], v[212:215], v[66:69]
	s_setprio 0
	s_setprio 1
	v_mfma_f32_16x16x32_bf16 v[30:33], v[146:149], v[172:175], v[30:33]
	v_mfma_f32_16x16x32_bf16 v[26:29], v[154:157], v[172:175], v[26:29]
	v_mfma_f32_16x16x32_bf16 v[22:25], v[146:149], v[180:183], v[22:25]
	v_mfma_f32_16x16x32_bf16 v[18:21], v[154:157], v[180:183], v[18:21]
	v_mfma_f32_16x16x32_bf16 v[14:17], v[146:149], v[188:191], v[14:17]
	v_mfma_f32_16x16x32_bf16 v[10:13], v[154:157], v[188:191], v[10:13]
	v_mfma_f32_16x16x32_bf16 v[6:9], v[146:149], v[208:211], v[6:9]
	v_mfma_f32_16x16x32_bf16 v[2:5], v[154:157], v[208:211], v[2:5]
	v_mfma_f32_16x16x32_bf16 v[30:33], v[150:153], v[176:179], v[30:33]
	v_mfma_f32_16x16x32_bf16 v[26:29], v[158:161], v[176:179], v[26:29]
	v_mfma_f32_16x16x32_bf16 v[22:25], v[150:153], v[184:187], v[22:25]
	v_mfma_f32_16x16x32_bf16 v[18:21], v[158:161], v[184:187], v[18:21]
	v_mfma_f32_16x16x32_bf16 v[14:17], v[150:153], v[192:195], v[14:17]
	v_mfma_f32_16x16x32_bf16 v[10:13], v[158:161], v[192:195], v[10:13]
	v_mfma_f32_16x16x32_bf16 v[6:9], v[150:153], v[212:215], v[6:9]
	v_mfma_f32_16x16x32_bf16 v[2:5], v[158:161], v[212:215], v[2:5]
	s_setprio 0
	s_add_u32 s19, s19, 0x100
	s_addc_u32 s42, s42, 0
	s_add_u32 s4, s4, 0x100
	s_addc_u32 s5, s5, 0
	s_mov_b32 s14, s15
	s_add_i32 s15, s14, 2
	s_add_u32 s6, s4, 0x80
	s_addc_u32 s7, s5, 0
	s_add_i32 s40, 0, 0x10000
	s_cmp_eq_u32 s10, s14
	s_cselect_b32 s39, s71, s7
	s_cselect_b32 s38, s70, s6
	s_cselect_b32 s7, s73, s42
	s_cselect_b32 s6, s72, s19
	s_add_i32 s14, 0, 0x14000
	v_add_u32_e32 v142, s40, v239
	v_add_u32_e32 v158, s14, v239
	s_cmp_gt_u32 s15, s11
	s_barrier
	s_cbranch_scc0 .Lkrot_371
	v_readlane_b32 s4, v253, 30
	v_readlane_b32 s5, v253, 31
	s_and_b64 vcc, exec, s[4:5]
	s_cbranch_vccz .LBB0_374
	s_barrier

.Lkrot_559:
	ds_read_b128 v[144:147], v0
	ds_read_b128 v[148:151], v0 offset:1024
	ds_read_b128 v[152:155], v0 offset:2048
	ds_read_b128 v[156:159], v0 offset:3072
	v_add_u32_e32 v0, s76, v167
	ds_read_b128 v[160:163], v0
	ds_read_b128 v[170:173], v0 offset:1024
	ds_read_b128 v[174:177], v0 offset:2048
	ds_read_b128 v[178:181], v0 offset:3072
	v_lshl_add_u64 v[164:165], s[4:5], 0, v[142:143]
	s_add_i32 m0, s11, 0xc000
	ds_read_b128 v[182:185], v169
	ds_read_b128 v[186:189], v169 offset:1024
	ds_read_b128 v[190:193], v169 offset:2048
	ds_read_b128 v[208:211], v169 offset:3072
	ds_read_b128 v[212:215], v169 offset:4096
	ds_read_b128 v[238:241], v169 offset:5120
	ds_read_b128 v[242:245], v169 offset:6144
	ds_read_b128 v[246:249], v169 offset:7168
	global_load_lds_dwordx4 v[164:165], off
	v_lshl_add_u64 v[164:165], s[4:5], 0, v[140:141]
	s_add_i32 m0, s11, 0xe000
	s_nop 0
	global_load_lds_dwordx4 v[164:165], off
	s_waitcnt vmcnt(8)
	s_waitcnt lgkmcnt(0)
	s_barrier
	s_setprio 1
	s_waitcnt lgkmcnt(0)
	v_mfma_f32_16x16x32_bf16 v[126:129], v[144:147], v[182:185], v[126:129]
	v_mfma_f32_16x16x32_bf16 v[122:125], v[152:155], v[182:185], v[122:125]
	v_mfma_f32_16x16x32_bf16 v[118:121], v[144:147], v[190:193], v[118:121]
	v_mfma_f32_16x16x32_bf16 v[114:117], v[152:155], v[190:193], v[114:117]
	v_mfma_f32_16x16x32_bf16 v[110:113], v[144:147], v[212:215], v[110:113]
	v_mfma_f32_16x16x32_bf16 v[106:109], v[152:155], v[212:215], v[106:109]
	v_mfma_f32_16x16x32_bf16 v[102:105], v[144:147], v[242:245], v[102:105]
	v_mfma_f32_16x16x32_bf16 v[98:101], v[152:155], v[242:245], v[98:101]
	v_mfma_f32_16x16x32_bf16 v[126:129], v[148:151], v[186:189], v[126:129]
	v_mfma_f32_16x16x32_bf16 v[122:125], v[156:159], v[186:189], v[122:125]
	v_mfma_f32_16x16x32_bf16 v[118:121], v[148:151], v[208:211], v[118:121]
	v_mfma_f32_16x16x32_bf16 v[114:117], v[156:159], v[208:211], v[114:117]
	v_mfma_f32_16x16x32_bf16 v[110:113], v[148:151], v[238:241], v[110:113]
	v_mfma_f32_16x16x32_bf16 v[106:109], v[156:159], v[238:241], v[106:109]
	v_mfma_f32_16x16x32_bf16 v[102:105], v[148:151], v[246:249], v[102:105]
	v_mfma_f32_16x16x32_bf16 v[98:101], v[156:159], v[246:249], v[98:101]
	s_setprio 0
	s_setprio 1
	v_mfma_f32_16x16x32_bf16 v[94:97], v[160:163], v[182:185], v[94:97]
	v_mfma_f32_16x16x32_bf16 v[90:93], v[174:177], v[182:185], v[90:93]
	v_mfma_f32_16x16x32_bf16 v[86:89], v[160:163], v[190:193], v[86:89]
	v_mfma_f32_16x16x32_bf16 v[82:85], v[174:177], v[190:193], v[82:85]
	v_mfma_f32_16x16x32_bf16 v[78:81], v[160:163], v[212:215], v[78:81]
	v_mfma_f32_16x16x32_bf16 v[74:77], v[174:177], v[212:215], v[74:77]
	v_mfma_f32_16x16x32_bf16 v[70:73], v[160:163], v[242:245], v[70:73]
	v_mfma_f32_16x16x32_bf16 v[66:69], v[174:177], v[242:245], v[66:69]
	v_mfma_f32_16x16x32_bf16 v[94:97], v[170:173], v[186:189], v[94:97]
	v_mfma_f32_16x16x32_bf16 v[90:93], v[178:181], v[186:189], v[90:93]
	v_mfma_f32_16x16x32_bf16 v[86:89], v[170:173], v[208:211], v[86:89]
	v_mfma_f32_16x16x32_bf16 v[82:85], v[178:181], v[208:211], v[82:85]
	v_mfma_f32_16x16x32_bf16 v[78:81], v[170:173], v[238:241], v[78:81]
	v_mfma_f32_16x16x32_bf16 v[74:77], v[178:181], v[238:241], v[74:77]
	v_mfma_f32_16x16x32_bf16 v[70:73], v[170:173], v[246:249], v[70:73]
	v_mfma_f32_16x16x32_bf16 v[66:69], v[178:181], v[246:249], v[66:69]
	s_setprio 0
	s_barrier
	s_add_i32 s6, s15, s49
	v_lshl_add_u64 v[164:165], s[38:39], 0, v[134:135]
	s_mov_b32 m0, s6
	ds_read_b128 v[182:185], v169 offset:16384
	ds_read_b128 v[186:189], v169 offset:17408
	ds_read_b128 v[190:193], v169 offset:18432
	ds_read_b128 v[208:211], v169 offset:19456
	ds_read_b128 v[212:215], v169 offset:20480
	ds_read_b128 v[238:241], v169 offset:21504
	ds_read_b128 v[242:245], v169 offset:22528
	ds_read_b128 v[246:249], v169 offset:23552
	global_load_lds_dwordx4 v[164:165], off
	s_add_i32 m0, s6, 0x2000
	s_add_u32 s6, s38, 0x80000
	v_lshl_add_u64 v[194:195], s[38:39], 0, v[130:131]
	s_addc_u32 s7, s39, 0
	s_add_i32 s15, s76, s49
	global_load_lds_dwordx4 v[194:195], off
	v_lshl_add_u64 v[216:217], s[6:7], 0, v[134:135]
	s_mov_b32 m0, s15
	v_lshl_add_u64 v[250:251], s[40:41], 0, v[132:133]
	global_load_lds_dwordx4 v[216:217], off
	v_lshl_add_u64 v[216:217], s[6:7], 0, v[130:131]
	s_add_i32 m0, s15, 0x2000
	s_nop 0
	global_load_lds_dwordx4 v[216:217], off
	v_lshl_add_u64 v[216:217], s[40:41], 0, v[136:137]
	s_mov_b32 m0, s11
	s_nop 0
	global_load_lds_dwordx4 v[216:217], off
	s_mov_b32 m0, s42
	s_nop 0
	global_load_lds_dwordx4 v[250:251], off
	s_waitcnt vmcnt(8)
	s_waitcnt lgkmcnt(0)
	s_barrier
	s_setprio 1
	s_waitcnt lgkmcnt(0)
	v_mfma_f32_16x16x32_bf16 v[62:65], v[144:147], v[182:185], v[62:65]
	v_mfma_f32_16x16x32_bf16 v[58:61], v[152:155], v[182:185], v[58:61]
	v_mfma_f32_16x16x32_bf16 v[54:57], v[144:147], v[190:193], v[54:57]
	v_mfma_f32_16x16x32_bf16 v[50:53], v[152:155], v[190:193], v[50:53]
	v_mfma_f32_16x16x32_bf16 v[46:49], v[144:147], v[212:215], v[46:49]
	v_mfma_f32_16x16x32_bf16 v[42:45], v[152:155], v[212:215], v[42:45]
	v_mfma_f32_16x16x32_bf16 v[38:41], v[144:147], v[242:245], v[38:41]
	v_mfma_f32_16x16x32_bf16 v[34:37], v[152:155], v[242:245], v[34:37]
	v_mfma_f32_16x16x32_bf16 v[62:65], v[148:151], v[186:189], v[62:65]
	v_mfma_f32_16x16x32_bf16 v[58:61], v[156:159], v[186:189], v[58:61]
	v_mfma_f32_16x16x32_bf16 v[54:57], v[148:151], v[208:211], v[54:57]
	v_mfma_f32_16x16x32_bf16 v[50:53], v[156:159], v[208:211], v[50:53]
	v_mfma_f32_16x16x32_bf16 v[46:49], v[148:151], v[238:241], v[46:49]
	v_mfma_f32_16x16x32_bf16 v[42:45], v[156:159], v[238:241], v[42:45]
	v_mfma_f32_16x16x32_bf16 v[38:41], v[148:151], v[246:249], v[38:41]
	v_mfma_f32_16x16x32_bf16 v[34:37], v[156:159], v[246:249], v[34:37]
	s_setprio 0
	s_setprio 1
	v_mfma_f32_16x16x32_bf16 v[30:33], v[160:163], v[182:185], v[30:33]
	v_mfma_f32_16x16x32_bf16 v[26:29], v[174:177], v[182:185], v[26:29]
	v_mfma_f32_16x16x32_bf16 v[22:25], v[160:163], v[190:193], v[22:25]
	v_mfma_f32_16x16x32_bf16 v[18:21], v[174:177], v[190:193], v[18:21]
	v_mfma_f32_16x16x32_bf16 v[14:17], v[160:163], v[212:215], v[14:17]
	v_mfma_f32_16x16x32_bf16 v[10:13], v[174:177], v[212:215], v[10:13]
	v_mfma_f32_16x16x32_bf16 v[6:9], v[160:163], v[242:245], v[6:9]
	v_mfma_f32_16x16x32_bf16 v[2:5], v[174:177], v[242:245], v[2:5]
	v_mfma_f32_16x16x32_bf16 v[30:33], v[170:173], v[186:189], v[30:33]
	v_mfma_f32_16x16x32_bf16 v[26:29], v[178:181], v[186:189], v[26:29]
	v_mfma_f32_16x16x32_bf16 v[22:25], v[170:173], v[208:211], v[22:25]
	v_mfma_f32_16x16x32_bf16 v[18:21], v[178:181], v[208:211], v[18:21]
	v_mfma_f32_16x16x32_bf16 v[14:17], v[170:173], v[238:241], v[14:17]
	v_mfma_f32_16x16x32_bf16 v[10:13], v[178:181], v[238:241], v[10:13]
	v_mfma_f32_16x16x32_bf16 v[6:9], v[170:173], v[246:249], v[6:9]
	v_mfma_f32_16x16x32_bf16 v[2:5], v[178:181], v[246:249], v[2:5]
	s_setprio 0
	s_barrier
	s_add_i32 s15, 0, 0x18000
	v_add_u32_e32 v0, s15, v167
	s_add_i32 s76, 0, 0x1c000
	ds_read_b128 v[144:147], v0
	ds_read_b128 v[148:151], v0 offset:1024
	ds_read_b128 v[152:155], v0 offset:2048
	ds_read_b128 v[156:159], v0 offset:3072
	v_add_u32_e32 v0, s76, v167
	ds_read_b128 v[160:163], v0
	ds_read_b128 v[170:173], v0 offset:1024
	ds_read_b128 v[174:177], v0 offset:2048
	ds_read_b128 v[178:181], v0 offset:3072
	s_add_u32 s6, s40, 0x80000
	s_addc_u32 s7, s41, 0
	s_mov_b32 m0, s43
	v_lshl_add_u64 v[196:197], s[6:7], 0, v[136:137]
	ds_read_b128 v[182:185], v169 offset:32768
	ds_read_b128 v[186:189], v169 offset:33792
	ds_read_b128 v[190:193], v169 offset:34816
	ds_read_b128 v[208:211], v169 offset:35840
	ds_read_b128 v[212:215], v169 offset:36864
	ds_read_b128 v[238:241], v169 offset:37888
	ds_read_b128 v[242:245], v169 offset:38912
	ds_read_b128 v[246:249], v169 offset:39936
	global_load_lds_dwordx4 v[196:197], off
	v_lshl_add_u64 v[196:197], s[6:7], 0, v[132:133]
	s_mov_b32 m0, s44
	s_nop 0
	global_load_lds_dwordx4 v[196:197], off
	s_waitcnt vmcnt(8)
	s_waitcnt lgkmcnt(0)
	s_barrier
	s_setprio 1
	s_waitcnt lgkmcnt(0)
	v_mfma_f32_16x16x32_bf16 v[126:129], v[144:147], v[182:185], v[126:129]
	v_mfma_f32_16x16x32_bf16 v[122:125], v[152:155], v[182:185], v[122:125]
	v_mfma_f32_16x16x32_bf16 v[118:121], v[144:147], v[190:193], v[118:121]
	v_mfma_f32_16x16x32_bf16 v[114:117], v[152:155], v[190:193], v[114:117]
	v_mfma_f32_16x16x32_bf16 v[110:113], v[144:147], v[212:215], v[110:113]
	v_mfma_f32_16x16x32_bf16 v[106:109], v[152:155], v[212:215], v[106:109]
	v_mfma_f32_16x16x32_bf16 v[102:105], v[144:147], v[242:245], v[102:105]
	v_mfma_f32_16x16x32_bf16 v[98:101], v[152:155], v[242:245], v[98:101]
	v_mfma_f32_16x16x32_bf16 v[126:129], v[148:151], v[186:189], v[126:129]
	v_mfma_f32_16x16x32_bf16 v[122:125], v[156:159], v[186:189], v[122:125]
	v_mfma_f32_16x16x32_bf16 v[118:121], v[148:151], v[208:211], v[118:121]
	v_mfma_f32_16x16x32_bf16 v[114:117], v[156:159], v[208:211], v[114:117]
	v_mfma_f32_16x16x32_bf16 v[110:113], v[148:151], v[238:241], v[110:113]
	v_mfma_f32_16x16x32_bf16 v[106:109], v[156:159], v[238:241], v[106:109]
	v_mfma_f32_16x16x32_bf16 v[102:105], v[148:151], v[246:249], v[102:105]
	v_mfma_f32_16x16x32_bf16 v[98:101], v[156:159], v[246:249], v[98:101]
	s_setprio 0
	s_setprio 1
	v_mfma_f32_16x16x32_bf16 v[94:97], v[160:163], v[182:185], v[94:97]
	v_mfma_f32_16x16x32_bf16 v[90:93], v[174:177], v[182:185], v[90:93]
	v_mfma_f32_16x16x32_bf16 v[86:89], v[160:163], v[190:193], v[86:89]
	v_mfma_f32_16x16x32_bf16 v[82:85], v[174:177], v[190:193], v[82:85]
	v_mfma_f32_16x16x32_bf16 v[78:81], v[160:163], v[212:215], v[78:81]
	v_mfma_f32_16x16x32_bf16 v[74:77], v[174:177], v[212:215], v[74:77]
	v_mfma_f32_16x16x32_bf16 v[70:73], v[160:163], v[242:245], v[70:73]
	v_mfma_f32_16x16x32_bf16 v[66:69], v[174:177], v[242:245], v[66:69]
	v_mfma_f32_16x16x32_bf16 v[94:97], v[170:173], v[186:189], v[94:97]
	v_mfma_f32_16x16x32_bf16 v[90:93], v[178:181], v[186:189], v[90:93]
	v_mfma_f32_16x16x32_bf16 v[86:89], v[170:173], v[208:211], v[86:89]
	v_mfma_f32_16x16x32_bf16 v[82:85], v[178:181], v[208:211], v[82:85]
	v_mfma_f32_16x16x32_bf16 v[78:81], v[170:173], v[238:241], v[78:81]
	v_mfma_f32_16x16x32_bf16 v[74:77], v[178:181], v[238:241], v[74:77]
	v_mfma_f32_16x16x32_bf16 v[70:73], v[170:173], v[246:249], v[70:73]
	v_mfma_f32_16x16x32_bf16 v[66:69], v[178:181], v[246:249], v[66:69]
	s_setprio 0
	s_barrier
	s_add_i32 s6, s15, s49
	v_lshl_add_u64 v[164:165], v[164:165], 0, s[36:37]
	s_mov_b32 m0, s6
	ds_read_b128 v[182:185], v169 offset:49152
	ds_read_b128 v[186:189], v169 offset:50176
	ds_read_b128 v[190:193], v169 offset:51200
	ds_read_b128 v[208:211], v169 offset:52224
	ds_read_b128 v[212:215], v169 offset:53248
	ds_read_b128 v[238:241], v169 offset:54272
	ds_read_b128 v[242:245], v169 offset:55296
	ds_read_b128 v[246:249], v169 offset:56320
	global_load_lds_dwordx4 v[164:165], off
	s_add_i32 m0, s6, 0x2000
	s_add_u32 s6, s38, 0x80080
	v_lshl_add_u64 v[164:165], v[194:195], 0, s[36:37]
	s_addc_u32 s7, s39, 0
	s_add_i32 s15, s76, s49
	global_load_lds_dwordx4 v[164:165], off
	v_lshl_add_u64 v[164:165], s[6:7], 0, v[134:135]
	s_mov_b32 m0, s15
	s_nop 0
	global_load_lds_dwordx4 v[164:165], off
	v_lshl_add_u64 v[164:165], s[6:7], 0, v[130:131]
	s_add_i32 m0, s15, 0x2000
	s_nop 0
	global_load_lds_dwordx4 v[164:165], off
	v_lshl_add_u64 v[164:165], v[216:217], 0, s[36:37]
	s_mov_b32 m0, s45
	s_nop 0
	global_load_lds_dwordx4 v[164:165], off
	v_lshl_add_u64 v[164:165], v[250:251], 0, s[36:37]
	s_mov_b32 m0, s78
	s_nop 0
	global_load_lds_dwordx4 v[164:165], off
	s_waitcnt vmcnt(8)
	s_waitcnt lgkmcnt(0)
	s_barrier
	s_setprio 1
	s_waitcnt lgkmcnt(0)
	v_mfma_f32_16x16x32_bf16 v[62:65], v[144:147], v[182:185], v[62:65]
	v_mfma_f32_16x16x32_bf16 v[58:61], v[152:155], v[182:185], v[58:61]
	v_mfma_f32_16x16x32_bf16 v[54:57], v[144:147], v[190:193], v[54:57]
	v_mfma_f32_16x16x32_bf16 v[50:53], v[152:155], v[190:193], v[50:53]
	v_mfma_f32_16x16x32_bf16 v[46:49], v[144:147], v[212:215], v[46:49]
	v_mfma_f32_16x16x32_bf16 v[42:45], v[152:155], v[212:215], v[42:45]
	v_mfma_f32_16x16x32_bf16 v[38:41], v[144:147], v[242:245], v[38:41]
	v_mfma_f32_16x16x32_bf16 v[34:37], v[152:155], v[242:245], v[34:37]
	v_mfma_f32_16x16x32_bf16 v[62:65], v[148:151], v[186:189], v[62:65]
	v_mfma_f32_16x16x32_bf16 v[58:61], v[156:159], v[186:189], v[58:61]
	v_mfma_f32_16x16x32_bf16 v[54:57], v[148:151], v[208:211], v[54:57]
	v_mfma_f32_16x16x32_bf16 v[50:53], v[156:159], v[208:211], v[50:53]
	v_mfma_f32_16x16x32_bf16 v[46:49], v[148:151], v[238:241], v[46:49]
	v_mfma_f32_16x16x32_bf16 v[42:45], v[156:159], v[238:241], v[42:45]
	v_mfma_f32_16x16x32_bf16 v[38:41], v[148:151], v[246:249], v[38:41]
	v_mfma_f32_16x16x32_bf16 v[34:37], v[156:159], v[246:249], v[34:37]
	s_setprio 0
	s_setprio 1
	v_mfma_f32_16x16x32_bf16 v[30:33], v[160:163], v[182:185], v[30:33]
	v_mfma_f32_16x16x32_bf16 v[26:29], v[174:177], v[182:185], v[26:29]
	v_mfma_f32_16x16x32_bf16 v[22:25], v[160:163], v[190:193], v[22:25]
	v_mfma_f32_16x16x32_bf16 v[18:21], v[174:177], v[190:193], v[18:21]
	v_mfma_f32_16x16x32_bf16 v[14:17], v[160:163], v[212:215], v[14:17]
	v_mfma_f32_16x16x32_bf16 v[10:13], v[174:177], v[212:215], v[10:13]
	v_mfma_f32_16x16x32_bf16 v[6:9], v[160:163], v[242:245], v[6:9]
	v_mfma_f32_16x16x32_bf16 v[2:5], v[174:177], v[242:245], v[2:5]
	v_mfma_f32_16x16x32_bf16 v[30:33], v[170:173], v[186:189], v[30:33]
	v_mfma_f32_16x16x32_bf16 v[26:29], v[178:181], v[186:189], v[26:29]
	v_mfma_f32_16x16x32_bf16 v[22:25], v[170:173], v[208:211], v[22:25]
	v_mfma_f32_16x16x32_bf16 v[18:21], v[178:181], v[208:211], v[18:21]
	v_mfma_f32_16x16x32_bf16 v[14:17], v[170:173], v[238:241], v[14:17]
	v_mfma_f32_16x16x32_bf16 v[10:13], v[178:181], v[238:241], v[10:13]
	v_mfma_f32_16x16x32_bf16 v[6:9], v[170:173], v[246:249], v[6:9]
	v_mfma_f32_16x16x32_bf16 v[2:5], v[178:181], v[246:249], v[2:5]
	s_setprio 0
	s_add_i32 s14, s14, 2
	s_add_u32 vcc_lo, vcc_lo, 0x100
	s_addc_u32 vcc_hi, vcc_hi, 0
	s_add_u32 s4, s4, 0x100
	s_addc_u32 s5, s5, 0
	s_add_u32 s6, s4, 0xfff80080
	s_addc_u32 s7, s5, -1
	s_add_i32 s15, 0, 0x10000
	s_cmp_eq_u32 s14, 28
	s_cselect_b32 s41, s8, s7
	s_cselect_b32 s40, s9, s6
	v_add_u32_e32 v0, s15, v167
	s_cselect_b32 s39, s71, vcc_hi
	s_cselect_b32 s38, s73, vcc_lo
	s_add_i32 s76, 0, 0x14000
	s_cmp_gt_u32 s14, 29
	s_barrier
	s_cbranch_scc0 .Lkrot_559
	s_lshl_b32 s8, s94, 8
	s_add_i32 s8, s8, s12
	s_cmp_lt_i32 s95, 10
	v_or_b32_e32 v144, s8, v166
	s_mov_b64 s[40:41], -1
	s_mov_b64 s[4:5], 0
	s_cbranch_scc1 .LBB0_569
	v_readlane_b32 s76, v252, 59
	s_cmp_gt_i32 s95, 17
	s_mov_b64 s[38:39], 0
	v_readlane_b32 s77, v252, 60
	s_cbranch_scc0 .LBB0_566
	s_cmp_eq_u32 s95, 18
	s_mov_b64 s[38:39], -1
	s_cbranch_scc0 .LBB0_670
	s_andn2_b64 vcc, exec, s[20:21]
	s_cbranch_vccnz .LBB0_565
	v_or_b32_e32 v148, 16, v144
	v_ashrrev_i32_e32 v145, 31, v144
	v_ashrrev_i32_e32 v149, 31, v148
	v_lshlrev_b64 v[146:147], 7, v[144:145]
	v_lshlrev_b64 v[148:149], 7, v[148:149]
	v_lshl_add_u64 v[146:147], v[138:139], 0, v[146:147]
	v_lshl_add_u64 v[148:149], v[138:139], 0, v[148:149]
	flat_store_dwordx4 v[146:147], v[126:129]
	flat_store_dwordx4 v[146:147], v[122:125] offset:16
	flat_store_dwordx4 v[148:149], v[118:121]
	flat_store_dwordx4 v[148:149], v[114:117] offset:16
	v_or_b32_e32 v148, 32, v144
	v_ashrrev_i32_e32 v149, 31, v148
	v_lshlrev_b64 v[148:149], 7, v[148:149]
	v_lshl_add_u64 v[148:149], v[138:139], 0, v[148:149]
	flat_store_dwordx4 v[148:149], v[110:113]
	flat_store_dwordx4 v[148:149], v[106:109] offset:16
	v_or_b32_e32 v148, 48, v144
	v_ashrrev_i32_e32 v149, 31, v148
	v_lshlrev_b64 v[148:149], 7, v[148:149]
	v_lshl_add_u64 v[148:149], v[138:139], 0, v[148:149]
	s_mov_b64 s[14:15], 0x4000
	v_add_co_u32_e32 v150, vcc, 0x4000, v146
	flat_store_dwordx4 v[148:149], v[102:105]
	flat_store_dwordx4 v[148:149], v[98:101] offset:16
	v_lshl_add_u64 v[148:149], v[146:147], 0, s[14:15]
	v_addc_co_u32_e32 v151, vcc, 0, v147, vcc
	s_mov_b64 s[14:15], 0x4800
	flat_store_dwordx4 v[150:151], v[62:65]
	flat_store_dwordx4 v[148:149], v[58:61] offset:16
	v_lshl_add_u64 v[148:149], v[146:147], 0, s[14:15]
	flat_store_dwordx4 v[150:151], v[54:57] offset:2048
	flat_store_dwordx4 v[148:149], v[50:53] offset:16
	v_add_co_u32_e32 v150, vcc, 0x5000, v146
	s_mov_b64 s[14:15], 0x5000
	s_nop 0
	v_addc_co_u32_e32 v151, vcc, 0, v147, vcc
	s_mov_b64 s[6:7], 0x5800
	v_lshl_add_u64 v[148:149], v[146:147], 0, s[14:15]
	flat_store_dwordx4 v[150:151], v[46:49]
	flat_store_dwordx4 v[148:149], v[42:45] offset:16
	v_lshl_add_u64 v[146:147], v[146:147], 0, s[6:7]
	flat_store_dwordx4 v[150:151], v[38:41] offset:2048
	flat_store_dwordx4 v[146:147], v[34:37] offset:16
